# SwiGLU epilogue software-pipelined across row groups (exp/rcp of one group interleaved with packed multiplies / conversions / store of its neighbours)
# speedup vs baseline: 1.0013x; 1.0013x over previous
; __device__ __forceinline__ unsigned pk2(float lo, float hi) { f32x2_t v = {lo, hi}; bf16x2_t b = __builtin_convertvector(v, bf16x2_t); return __builtin_bit_cast(unsigned, b); }
; __device__ __forceinline__ float fast_sigmoid(float x) { return __builtin_amdgcn_rcpf(1.0f + __builtin_amdgcn_exp2f(-x * LOG2E)); }
; __device__ __forceinline__ void epi_all_run(const void* Pk_, int l, int s, const f32x4 (&acc)[2][2][4][2], const pg8::Unit& u, int wr, int wc, int fr, int fq) {
;     ...
;         if (s == 0 || s == 5) {
;             bf16_t* O = (bf16_t*)(ws + WS_ACT);
;             const int col0 = u.pn * 128 + wc * 32 + 8 * fq;
; #pragma unroll
;             for (int ai = 0; ai < 2; ++ai)
; #pragma unroll
;                 for (int m = 0; m < 4; ++m) {
;                     bf16_t* rowp = O + (size_t)(row0 + ai * 128 + m * 16) * DFF + col0;
;                     float r[8];
; #pragma unroll
;                     for (int n = 0; n < 2; ++n)
; #pragma unroll
;                         for (int j = 0; j < 4; ++j) { const float g = acc[ai][0][m][n][j], up = acc[ai][1][m][n][j]; r[n * 4 + j] = g * fast_sigmoid(g) * up; }
;                     v4u w; w.x = pk2(r[0], r[1]); w.y = pk2(r[2], r[3]); w.z = pk2(r[4], r[5]); w.w = pk2(r[6], r[7]);
;                     *(v4u*)rowp = w;
;                 }
.LBB0_125:
	s_and_b64 vcc, exec, s[38:39]
	s_cbranch_vccz .LBB0_124
	s_waitcnt lgkmcnt(0)
	v_lshl_or_b32 v130, s30, 7, v228
	s_mov_b32 s6, 0xbfb8aa3b
	v_ashrrev_i32_e32 v131, 31, v130
	s_mov_b64 s[4:5], 0x9500000
	v_lshl_add_u64 v[130:131], v[130:131], 1, s[34:35]
	s_movk_i32 s20, 0x1600
	v_lshl_add_u64 v[130:131], v[130:131], 0, s[4:5]
	v_pk_mul_f32 v[118:119], v[118:119], v[126:127]
	v_pk_mul_f32 v[120:121], v[120:121], v[128:129]
	v_pk_mul_f32 v[114:115], v[114:115], v[122:123]
	v_pk_mul_f32 v[116:117], v[116:117], v[124:125]
	v_pk_mul_f32 v[126:127], v[126:127], s[6:7] op_sel_hi:[1,0]
	v_pk_mul_f32 v[128:129], v[128:129], s[6:7] op_sel_hi:[1,0]
	v_pk_mul_f32 v[122:123], v[122:123], s[6:7] op_sel_hi:[1,0]
	v_pk_mul_f32 v[124:125], v[124:125], s[6:7] op_sel_hi:[1,0]
	v_exp_f32_e32 v126, v126
	v_exp_f32_e32 v127, v127
	v_exp_f32_e32 v128, v128
	v_exp_f32_e32 v129, v129
	v_exp_f32_e32 v122, v122
	v_exp_f32_e32 v123, v123
	v_exp_f32_e32 v124, v124
	v_exp_f32_e32 v125, v125
	v_pk_add_f32 v[126:127], v[126:127], 1.0 op_sel_hi:[1,0]
	v_pk_add_f32 v[128:129], v[128:129], 1.0 op_sel_hi:[1,0]
	v_pk_add_f32 v[122:123], v[122:123], 1.0 op_sel_hi:[1,0]
	v_pk_add_f32 v[124:125], v[124:125], 1.0 op_sel_hi:[1,0]
	v_rcp_f32_e32 v126, v126
	v_pk_mul_f32 v[102:103], v[102:103], v[110:111]
	v_rcp_f32_e32 v127, v127
	v_pk_mul_f32 v[104:105], v[104:105], v[112:113]
	v_rcp_f32_e32 v128, v128
	v_pk_mul_f32 v[98:99], v[98:99], v[106:107]
	v_rcp_f32_e32 v129, v129
	v_pk_mul_f32 v[100:101], v[100:101], v[108:109]
	v_rcp_f32_e32 v122, v122
	v_pk_mul_f32 v[110:111], v[110:111], s[6:7] op_sel_hi:[1,0]
	v_rcp_f32_e32 v123, v123
	v_pk_mul_f32 v[112:113], v[112:113], s[6:7] op_sel_hi:[1,0]
	v_rcp_f32_e32 v124, v124
	v_pk_mul_f32 v[106:107], v[106:107], s[6:7] op_sel_hi:[1,0]
	v_rcp_f32_e32 v125, v125
	v_pk_mul_f32 v[108:109], v[108:109], s[6:7] op_sel_hi:[1,0]
	v_exp_f32_e32 v110, v110
	v_pk_mul_f32 v[118:119], v[118:119], v[126:127]
	v_pk_mul_f32 v[120:121], v[120:121], v[128:129]
	v_exp_f32_e32 v111, v111
	v_pk_mul_f32 v[114:115], v[114:115], v[122:123]
	v_exp_f32_e32 v112, v112
	v_pk_mul_f32 v[116:117], v[116:117], v[124:125]
	v_exp_f32_e32 v113, v113
	v_cvt_pk_bf16_f32 v126, v118, v119
	v_exp_f32_e32 v106, v106
	v_cvt_pk_bf16_f32 v127, v120, v121
	v_cvt_pk_bf16_f32 v128, v114, v115
	v_exp_f32_e32 v107, v107
	v_cvt_pk_bf16_f32 v129, v116, v117
	v_exp_f32_e32 v108, v108
	v_mad_i64_i32 v[132:133], s[8:9], v184, s20, v[130:131]
	v_exp_f32_e32 v109, v109
	global_store_dwordx4 v[132:133], v[126:129], off
	v_pk_add_f32 v[110:111], v[110:111], 1.0 op_sel_hi:[1,0]
	v_pk_add_f32 v[112:113], v[112:113], 1.0 op_sel_hi:[1,0]
	v_pk_add_f32 v[106:107], v[106:107], 1.0 op_sel_hi:[1,0]
	v_pk_add_f32 v[108:109], v[108:109], 1.0 op_sel_hi:[1,0]
	v_rcp_f32_e32 v110, v110
	v_pk_mul_f32 v[86:87], v[86:87], v[94:95]
	v_rcp_f32_e32 v111, v111
	v_pk_mul_f32 v[88:89], v[88:89], v[96:97]
	v_rcp_f32_e32 v112, v112
	v_pk_mul_f32 v[82:83], v[82:83], v[90:91]
	v_rcp_f32_e32 v113, v113
	v_pk_mul_f32 v[84:85], v[84:85], v[92:93]
	v_rcp_f32_e32 v106, v106
	v_pk_mul_f32 v[94:95], v[94:95], s[6:7] op_sel_hi:[1,0]
	v_rcp_f32_e32 v107, v107
	v_pk_mul_f32 v[96:97], v[96:97], s[6:7] op_sel_hi:[1,0]
	v_rcp_f32_e32 v108, v108
	v_pk_mul_f32 v[90:91], v[90:91], s[6:7] op_sel_hi:[1,0]
	v_rcp_f32_e32 v109, v109
	v_pk_mul_f32 v[92:93], v[92:93], s[6:7] op_sel_hi:[1,0]
	v_exp_f32_e32 v94, v94
	v_pk_mul_f32 v[102:103], v[102:103], v[110:111]
	v_pk_mul_f32 v[104:105], v[104:105], v[112:113]
	v_exp_f32_e32 v95, v95
	v_pk_mul_f32 v[98:99], v[98:99], v[106:107]
	v_exp_f32_e32 v96, v96
	v_pk_mul_f32 v[100:101], v[100:101], v[108:109]
	v_exp_f32_e32 v97, v97
	v_cvt_pk_bf16_f32 v110, v102, v103
	v_exp_f32_e32 v90, v90
	v_cvt_pk_bf16_f32 v111, v104, v105
	v_cvt_pk_bf16_f32 v112, v98, v99
	v_exp_f32_e32 v91, v91
	v_cvt_pk_bf16_f32 v113, v100, v101
	v_exp_f32_e32 v92, v92
	v_mad_i64_i32 v[132:133], s[8:9], v186, s20, v[130:131]
	v_exp_f32_e32 v93, v93
	global_store_dwordx4 v[132:133], v[110:113], off
	v_pk_add_f32 v[94:95], v[94:95], 1.0 op_sel_hi:[1,0]
	v_pk_add_f32 v[96:97], v[96:97], 1.0 op_sel_hi:[1,0]
	v_pk_add_f32 v[90:91], v[90:91], 1.0 op_sel_hi:[1,0]
	v_pk_add_f32 v[92:93], v[92:93], 1.0 op_sel_hi:[1,0]
	v_rcp_f32_e32 v94, v94
	v_pk_mul_f32 v[70:71], v[70:71], v[78:79]
	v_rcp_f32_e32 v95, v95
	v_pk_mul_f32 v[72:73], v[72:73], v[80:81]
	v_rcp_f32_e32 v96, v96
	v_pk_mul_f32 v[66:67], v[66:67], v[74:75]
	v_rcp_f32_e32 v97, v97
	v_pk_mul_f32 v[68:69], v[68:69], v[76:77]
	v_rcp_f32_e32 v90, v90
	v_pk_mul_f32 v[78:79], v[78:79], s[6:7] op_sel_hi:[1,0]
	v_rcp_f32_e32 v91, v91
	v_pk_mul_f32 v[80:81], v[80:81], s[6:7] op_sel_hi:[1,0]
	v_rcp_f32_e32 v92, v92
	v_pk_mul_f32 v[74:75], v[74:75], s[6:7] op_sel_hi:[1,0]
	v_rcp_f32_e32 v93, v93
	v_pk_mul_f32 v[76:77], v[76:77], s[6:7] op_sel_hi:[1,0]
	v_exp_f32_e32 v78, v78
	v_pk_mul_f32 v[86:87], v[86:87], v[94:95]
	v_pk_mul_f32 v[88:89], v[88:89], v[96:97]
	v_exp_f32_e32 v79, v79
	v_pk_mul_f32 v[82:83], v[82:83], v[90:91]
	v_exp_f32_e32 v80, v80
	v_pk_mul_f32 v[84:85], v[84:85], v[92:93]
	v_cvt_pk_bf16_f32 v94, v86, v87
	v_exp_f32_e32 v81, v81
	v_cvt_pk_bf16_f32 v95, v88, v89
	v_exp_f32_e32 v74, v74
	v_cvt_pk_bf16_f32 v96, v82, v83
	v_exp_f32_e32 v75, v75
	v_cvt_pk_bf16_f32 v97, v84, v85
	v_or_b32_e32 v86, 32, v184
	v_exp_f32_e32 v76, v76
	v_mad_i64_i32 v[132:133], s[8:9], v86, s20, v[130:131]
	v_exp_f32_e32 v77, v77
	global_store_dwordx4 v[132:133], v[94:97], off
	v_pk_add_f32 v[78:79], v[78:79], 1.0 op_sel_hi:[1,0]
	v_pk_add_f32 v[80:81], v[80:81], 1.0 op_sel_hi:[1,0]
	v_pk_add_f32 v[74:75], v[74:75], 1.0 op_sel_hi:[1,0]
	v_pk_add_f32 v[76:77], v[76:77], 1.0 op_sel_hi:[1,0]
; __device__ __forceinline__ unsigned pk2(float lo, float hi) { f32x2_t v = {lo, hi}; bf16x2_t b = __builtin_convertvector(v, bf16x2_t); return __builtin_bit_cast(unsigned, b); }
; __device__ __forceinline__ float fast_sigmoid(float x) { return __builtin_amdgcn_rcpf(1.0f + __builtin_amdgcn_exp2f(-x * LOG2E)); }
; __device__ __forceinline__ void epi_all_run(const void* Pk_, int l, int s, const f32x4 (&acc)[2][2][4][2], const pg8::Unit& u, int wr, int wc, int fr, int fq) {
;     ...
;         if (s == 0 || s == 5) {
;             bf16_t* O = (bf16_t*)(ws + WS_ACT);
;             const int col0 = u.pn * 128 + wc * 32 + 8 * fq;
; #pragma unroll
;             for (int ai = 0; ai < 2; ++ai)
; #pragma unroll
;                 for (int m = 0; m < 4; ++m) {
;                     bf16_t* rowp = O + (size_t)(row0 + ai * 128 + m * 16) * DFF + col0;
;                     float r[8];
; #pragma unroll
;                     for (int n = 0; n < 2; ++n)
; #pragma unroll
;                         for (int j = 0; j < 4; ++j) { const float g = acc[ai][0][m][n][j], up = acc[ai][1][m][n][j]; r[n * 4 + j] = g * fast_sigmoid(g) * up; }
;                     v4u w; w.x = pk2(r[0], r[1]); w.y = pk2(r[2], r[3]); w.z = pk2(r[4], r[5]); w.w = pk2(r[6], r[7]);
;                     *(v4u*)rowp = w;
;                 }
	v_rcp_f32_e32 v78, v78
	v_pk_mul_f32 v[54:55], v[54:55], v[62:63]
	v_rcp_f32_e32 v79, v79
	v_pk_mul_f32 v[56:57], v[56:57], v[64:65]
	v_rcp_f32_e32 v80, v80
	v_pk_mul_f32 v[50:51], v[50:51], v[58:59]
	v_rcp_f32_e32 v81, v81
	v_pk_mul_f32 v[52:53], v[52:53], v[60:61]
	v_rcp_f32_e32 v74, v74
	v_pk_mul_f32 v[62:63], v[62:63], s[6:7] op_sel_hi:[1,0]
	v_rcp_f32_e32 v75, v75
	v_pk_mul_f32 v[64:65], v[64:65], s[6:7] op_sel_hi:[1,0]
	v_rcp_f32_e32 v76, v76
	v_pk_mul_f32 v[58:59], v[58:59], s[6:7] op_sel_hi:[1,0]
	v_rcp_f32_e32 v77, v77
	v_pk_mul_f32 v[60:61], v[60:61], s[6:7] op_sel_hi:[1,0]
	v_exp_f32_e32 v62, v62
	v_pk_mul_f32 v[70:71], v[70:71], v[78:79]
	v_pk_mul_f32 v[72:73], v[72:73], v[80:81]
	v_exp_f32_e32 v63, v63
	v_pk_mul_f32 v[66:67], v[66:67], v[74:75]
	v_exp_f32_e32 v64, v64
	v_pk_mul_f32 v[68:69], v[68:69], v[76:77]
	v_cvt_pk_bf16_f32 v78, v70, v71
	v_exp_f32_e32 v65, v65
	v_cvt_pk_bf16_f32 v79, v72, v73
	v_exp_f32_e32 v58, v58
	v_cvt_pk_bf16_f32 v80, v66, v67
	v_exp_f32_e32 v59, v59
	v_cvt_pk_bf16_f32 v81, v68, v69
	v_or_b32_e32 v70, 48, v184
	v_exp_f32_e32 v60, v60
	v_mad_i64_i32 v[132:133], s[8:9], v70, s20, v[130:131]
	v_exp_f32_e32 v61, v61
	global_store_dwordx4 v[132:133], v[78:81], off
	v_pk_add_f32 v[62:63], v[62:63], 1.0 op_sel_hi:[1,0]
	v_pk_add_f32 v[64:65], v[64:65], 1.0 op_sel_hi:[1,0]
	v_pk_add_f32 v[58:59], v[58:59], 1.0 op_sel_hi:[1,0]
	v_pk_add_f32 v[60:61], v[60:61], 1.0 op_sel_hi:[1,0]
	v_rcp_f32_e32 v62, v62
	v_pk_mul_f32 v[38:39], v[38:39], v[46:47]
	v_rcp_f32_e32 v63, v63
	v_pk_mul_f32 v[40:41], v[40:41], v[48:49]
	v_rcp_f32_e32 v64, v64
	v_pk_mul_f32 v[34:35], v[34:35], v[42:43]
	v_rcp_f32_e32 v65, v65
	v_pk_mul_f32 v[36:37], v[36:37], v[44:45]
	v_rcp_f32_e32 v58, v58
	v_pk_mul_f32 v[46:47], v[46:47], s[6:7] op_sel_hi:[1,0]
	v_rcp_f32_e32 v59, v59
	v_pk_mul_f32 v[48:49], v[48:49], s[6:7] op_sel_hi:[1,0]
	v_rcp_f32_e32 v60, v60
	v_pk_mul_f32 v[42:43], v[42:43], s[6:7] op_sel_hi:[1,0]
	v_rcp_f32_e32 v61, v61
	v_pk_mul_f32 v[44:45], v[44:45], s[6:7] op_sel_hi:[1,0]
	v_exp_f32_e32 v46, v46
	v_pk_mul_f32 v[54:55], v[54:55], v[62:63]
	v_pk_mul_f32 v[56:57], v[56:57], v[64:65]
	v_exp_f32_e32 v47, v47
	v_pk_mul_f32 v[50:51], v[50:51], v[58:59]
	v_exp_f32_e32 v48, v48
	v_pk_mul_f32 v[52:53], v[52:53], v[60:61]
	v_cvt_pk_bf16_f32 v62, v54, v55
	v_exp_f32_e32 v49, v49
	v_cvt_pk_bf16_f32 v63, v56, v57
	v_exp_f32_e32 v42, v42
	v_cvt_pk_bf16_f32 v64, v50, v51
	v_exp_f32_e32 v43, v43
	v_cvt_pk_bf16_f32 v65, v52, v53
	v_add_u32_e32 v54, 0x80, v184
	v_exp_f32_e32 v44, v44
	v_mad_i64_i32 v[132:133], s[8:9], v54, s20, v[130:131]
	v_exp_f32_e32 v45, v45
	global_store_dwordx4 v[132:133], v[62:65], off
	v_pk_add_f32 v[46:47], v[46:47], 1.0 op_sel_hi:[1,0]
	v_pk_add_f32 v[48:49], v[48:49], 1.0 op_sel_hi:[1,0]
	v_pk_add_f32 v[42:43], v[42:43], 1.0 op_sel_hi:[1,0]
	v_pk_add_f32 v[44:45], v[44:45], 1.0 op_sel_hi:[1,0]
	v_rcp_f32_e32 v46, v46
	v_pk_mul_f32 v[22:23], v[22:23], v[30:31]
	v_rcp_f32_e32 v47, v47
	v_pk_mul_f32 v[24:25], v[24:25], v[32:33]
	v_rcp_f32_e32 v48, v48
	v_pk_mul_f32 v[18:19], v[18:19], v[26:27]
	v_rcp_f32_e32 v49, v49
	v_pk_mul_f32 v[20:21], v[20:21], v[28:29]
	v_rcp_f32_e32 v42, v42
	v_pk_mul_f32 v[30:31], v[30:31], s[6:7] op_sel_hi:[1,0]
	v_rcp_f32_e32 v43, v43
	v_pk_mul_f32 v[32:33], v[32:33], s[6:7] op_sel_hi:[1,0]
	v_rcp_f32_e32 v44, v44
	v_pk_mul_f32 v[26:27], v[26:27], s[6:7] op_sel_hi:[1,0]
	v_rcp_f32_e32 v45, v45
	v_pk_mul_f32 v[28:29], v[28:29], s[6:7] op_sel_hi:[1,0]
	v_exp_f32_e32 v30, v30
	v_pk_mul_f32 v[38:39], v[38:39], v[46:47]
	v_pk_mul_f32 v[40:41], v[40:41], v[48:49]
	v_exp_f32_e32 v31, v31
	v_pk_mul_f32 v[34:35], v[34:35], v[42:43]
	v_exp_f32_e32 v32, v32
	v_pk_mul_f32 v[36:37], v[36:37], v[44:45]
	v_cvt_pk_bf16_f32 v46, v38, v39
	v_exp_f32_e32 v33, v33
	v_cvt_pk_bf16_f32 v47, v40, v41
	v_exp_f32_e32 v26, v26
	v_cvt_pk_bf16_f32 v48, v34, v35
	v_exp_f32_e32 v27, v27
	v_cvt_pk_bf16_f32 v49, v36, v37
	v_add_u32_e32 v38, 0x90, v184
	v_exp_f32_e32 v28, v28
	v_mad_i64_i32 v[132:133], s[8:9], v38, s20, v[130:131]
	v_exp_f32_e32 v29, v29
	global_store_dwordx4 v[132:133], v[46:49], off
	v_pk_add_f32 v[30:31], v[30:31], 1.0 op_sel_hi:[1,0]
	v_pk_add_f32 v[32:33], v[32:33], 1.0 op_sel_hi:[1,0]
	v_pk_add_f32 v[26:27], v[26:27], 1.0 op_sel_hi:[1,0]
	v_pk_add_f32 v[28:29], v[28:29], 1.0 op_sel_hi:[1,0]
	v_rcp_f32_e32 v30, v30
	v_pk_mul_f32 v[6:7], v[6:7], v[14:15]
	v_rcp_f32_e32 v31, v31
	v_pk_mul_f32 v[8:9], v[8:9], v[16:17]
	v_rcp_f32_e32 v32, v32
	v_pk_mul_f32 v[2:3], v[2:3], v[10:11]
	v_rcp_f32_e32 v33, v33
	v_pk_mul_f32 v[4:5], v[4:5], v[12:13]
	v_rcp_f32_e32 v26, v26
	v_pk_mul_f32 v[14:15], v[14:15], s[6:7] op_sel_hi:[1,0]
	v_rcp_f32_e32 v27, v27
	v_pk_mul_f32 v[16:17], v[16:17], s[6:7] op_sel_hi:[1,0]
	v_rcp_f32_e32 v28, v28
	v_pk_mul_f32 v[10:11], v[10:11], s[6:7] op_sel_hi:[1,0]
	v_rcp_f32_e32 v29, v29
	v_pk_mul_f32 v[12:13], v[12:13], s[6:7] op_sel_hi:[1,0]
	v_exp_f32_e32 v14, v14
	v_pk_mul_f32 v[22:23], v[22:23], v[30:31]
	v_pk_mul_f32 v[24:25], v[24:25], v[32:33]
	v_exp_f32_e32 v15, v15
	v_pk_mul_f32 v[18:19], v[18:19], v[26:27]
	v_exp_f32_e32 v16, v16
	v_pk_mul_f32 v[20:21], v[20:21], v[28:29]
	v_cvt_pk_bf16_f32 v30, v22, v23
	v_exp_f32_e32 v17, v17
	v_cvt_pk_bf16_f32 v31, v24, v25
	v_exp_f32_e32 v10, v10
	v_cvt_pk_bf16_f32 v32, v18, v19
	v_exp_f32_e32 v11, v11
	v_cvt_pk_bf16_f32 v33, v20, v21
	v_add_u32_e32 v22, 0xa0, v184
	v_exp_f32_e32 v12, v12
	v_mad_i64_i32 v[132:133], s[8:9], v22, s20, v[130:131]
	v_exp_f32_e32 v13, v13
	global_store_dwordx4 v[132:133], v[30:33], off
	v_pk_add_f32 v[14:15], v[14:15], 1.0 op_sel_hi:[1,0]
	v_pk_add_f32 v[16:17], v[16:17], 1.0 op_sel_hi:[1,0]
	v_pk_add_f32 v[10:11], v[10:11], 1.0 op_sel_hi:[1,0]
	v_pk_add_f32 v[12:13], v[12:13], 1.0 op_sel_hi:[1,0]
	v_rcp_f32_e32 v14, v14
	v_rcp_f32_e32 v15, v15
	v_rcp_f32_e32 v16, v16
	v_rcp_f32_e32 v17, v17
	v_rcp_f32_e32 v10, v10
	v_rcp_f32_e32 v11, v11
	v_rcp_f32_e32 v12, v12
	v_rcp_f32_e32 v13, v13
	v_pk_mul_f32 v[6:7], v[6:7], v[14:15]
	v_pk_mul_f32 v[8:9], v[8:9], v[16:17]
	v_pk_mul_f32 v[2:3], v[2:3], v[10:11]
	v_pk_mul_f32 v[4:5], v[4:5], v[12:13]
	v_cvt_pk_bf16_f32 v14, v6, v7
	v_cvt_pk_bf16_f32 v15, v8, v9
	v_cvt_pk_bf16_f32 v16, v2, v3
	v_cvt_pk_bf16_f32 v17, v4, v5
	v_add_u32_e32 v6, 0xb0, v184
	v_mad_i64_i32 v[132:133], s[8:9], v6, s20, v[130:131]
	global_store_dwordx4 v[132:133], v[14:17], off
	s_and_b64 vcc, exec, s[44:45]
	s_mov_b64 s[4:5], -1
	s_cbranch_vccnz .LBB0_51
